# v15: phase-2 gate operands: hi/lo bf16 split derives the rounded-high f32 from v_cvt_pk_bf16_f32 and feeds the MFMAs from the cvt destinations (no copy chain)
# speedup vs baseline: 1.0010x; 1.0010x over previous
; #define LAS __attribute__((address_space(3)))
; __device__ __forceinline__ float bf2f(unsigned b) { return __uint_as_float(b << 16); }
; __device__ __forceinline__ unsigned f2bf(float f) { unsigned u = __float_as_uint(f); return (u + 0x7fffu + ((u >> 16) & 1u)) >> 16; }
; __device__ __forceinline__ void split8(const f32x4 x0, const f32x4 x1, bf16x8& hi, bf16x8& lo) {
; #pragma unroll
;     for (int j = 0; j < 8; ++j) { const float x = j < 4 ? x0[j & 3] : x1[j & 3]; const unsigned h = f2bf(x); const unsigned l = f2bf(x - bf2f(h)); hi[j] = (short)h; lo[j] = (short)l; }
; }
; __device__ __forceinline__ void phase_gla_pre(const Params& P, LAS unsigned char* lds, bool dry) {
;     ...
;         __syncthreads();
;         float run = 0.f;
; #pragma unroll
;         for (int tt = 0; tt < 4; ++tt) {
;             bf16x8 ahi = (bf16x8){0, 0, 0, 0, 0, 0, 0, 0}, alo = ahi;
;             if (g < 2) { const f32x4 l0 = *(const LAS f32x4*)(Llr + (16 * tt + fr) * 16 + 8 * g), l1 = *(const LAS f32x4*)(Llr + (16 * tt + fr) * 16 + 8 * g + 4); split8(l0, l1, ahi, alo); }
.Lp2_join:
	v_mov_b32_e32 v33, 0
	v_mov_b32_e32 v34, 0
	v_mov_b32_e32 v35, 0
	v_mov_b32_e32 v36, 0
	v_mov_b32_e32 v37, 0
	v_mov_b32_e32 v38, 0
	v_mov_b32_e32 v39, 0
	s_waitcnt lgkmcnt(0)
	s_barrier
	v_mov_b32_e32 v100, 0
	v_mov_b32_e32 v101, 0
	v_mov_b32_e32 v102, 0
	v_mov_b32_e32 v103, 0
	v_mov_b32_e32 v104, 0
	v_mov_b32_e32 v105, 0
	v_mov_b32_e32 v106, 0
	v_mov_b32_e32 v107, 0
	s_and_saveexec_b64 s[36:37], s[6:7]
	s_cbranch_execz .LBB0_486
	ds_read_b128 v[30:33], v96
	ds_read_b128 v[34:37], v96 offset:16
	s_waitcnt lgkmcnt(1)
	v_cvt_pk_bf16_f32 v104, v30, v31
	v_lshlrev_b32_e32 v132, 16, v104
	v_and_b32_e32 v133, 0xffff0000, v104
	v_pk_add_f32 v[30:31], v[30:31], v[132:133] neg_lo:[0,1] neg_hi:[0,1]
	v_cvt_pk_bf16_f32 v105, v32, v33
	v_lshlrev_b32_e32 v134, 16, v105
	v_and_b32_e32 v135, 0xffff0000, v105
	v_pk_add_f32 v[32:33], v[32:33], v[134:135] neg_lo:[0,1] neg_hi:[0,1]
	s_waitcnt lgkmcnt(0)
	v_cvt_pk_bf16_f32 v106, v34, v35
	v_lshlrev_b32_e32 v136, 16, v106
	v_and_b32_e32 v137, 0xffff0000, v106
	v_pk_add_f32 v[34:35], v[34:35], v[136:137] neg_lo:[0,1] neg_hi:[0,1]
	v_cvt_pk_bf16_f32 v107, v36, v37
	v_lshlrev_b32_e32 v138, 16, v107
	v_and_b32_e32 v139, 0xffff0000, v107
	v_pk_add_f32 v[36:37], v[36:37], v[138:139] neg_lo:[0,1] neg_hi:[0,1]
	s_nop 0
	v_cvt_pk_bf16_f32 v103, v36, v37
	v_cvt_pk_bf16_f32 v102, v34, v35
	v_cvt_pk_bf16_f32 v101, v32, v33
	v_cvt_pk_bf16_f32 v100, v30, v31

; #define LAS __attribute__((address_space(3)))
; __device__ __forceinline__ float bf2f(unsigned b) { return __uint_as_float(b << 16); }
; __device__ __forceinline__ unsigned f2bf(float f) { unsigned u = __float_as_uint(f); return (u + 0x7fffu + ((u >> 16) & 1u)) >> 16; }
; __device__ __forceinline__ void split8(const f32x4 x0, const f32x4 x1, bf16x8& hi, bf16x8& lo) {
; #pragma unroll
;     for (int j = 0; j < 8; ++j) { const float x = j < 4 ? x0[j & 3] : x1[j & 3]; const unsigned h = f2bf(x); const unsigned l = f2bf(x - bf2f(h)); hi[j] = (short)h; lo[j] = (short)l; }
; }
; __device__ __forceinline__ void phase_gla_pre(const Params& P, LAS unsigned char* lds, bool dry) {
;     ...
;             if (g < 2) { const f32x4 l0 = *(const LAS f32x4*)(Llr + (16 * tt + fr) * 16 + 8 * g), l1 = *(const LAS f32x4*)(Llr + (16 * tt + fr) * 16 + 8 * g + 4); split8(l0, l1, ahi, alo); }
;             f32x4 acc = (f32x4){bg, bg, bg, bg};
;             acc = __builtin_amdgcn_mfma_f32_16x16x32_bf16(alo, bhi, acc, 0, 0, 0); acc = __builtin_amdgcn_mfma_f32_16x16x32_bf16(ahi, blo, acc, 0, 0, 0); acc = __builtin_amdgcn_mfma_f32_16x16x32_bf16(ahi, bhi, acc, 0, 0, 0);
;             float pr[4];
; #pragma unroll
;             for (int r = 0; r < 4; ++r) { const float lg = acc[r]; const float ls = fminf(lg, 0.f) - __logf(1.0f + __expf(-fabsf(lg))); pr[r] = ls * (1.0f / 16.0f) + (r ? pr[r - 1] : 0.f); }
;             const float T = pr[3];
;             const float u1 = __shfl_up(T, 16), s1 = T + (g >= 1 ? u1 : 0.f);
;             const float u2 = __shfl_up(s1, 32), s2 = s1 + (g >= 2 ? u2 : 0.f);
;             const float base = run + (s2 - T); run += __shfl(s2, 48 + fr);
; #pragma unroll
;             for (int r = 0; r < 4; ++r) *(LAS float*)(Lb + (16 * tt + 4 * g + r) * BP + (16 * w + fr) * 4) = base + pr[r];
.Lp2_nowait1:
	v_mov_b32_e32 v140, v20
	v_mov_b32_e32 v141, v21
	v_mov_b32_e32 v142, v22
	v_mov_b32_e32 v143, v23
	v_mov_b32_e32 v144, v24
	v_mov_b32_e32 v145, v25
	v_mov_b32_e32 v146, v26
	v_mov_b32_e32 v147, v27
	v_mov_b32_e32 v148, v28
	s_and_b32 s98, s38, 0xff
	s_cselect_b32 s98, 0, 1
	v_mov_b32_e32 v29, v28
	v_mov_b32_e32 v30, v28
	v_mov_b32_e32 v31, v28
	v_mov_b32_e32 v40, 0
	v_mov_b32_e32 v41, 0
	v_mfma_f32_16x16x32_bf16 v[32:35], v[100:103], v[20:23], v[28:31]
	v_mfma_f32_16x16x32_bf16 v[32:35], v[104:107], v[24:27], v[32:35]
	v_mfma_f32_16x16x32_bf16 v[32:35], v[104:107], v[20:23], v[32:35]
	s_nop 7
	v_max_f32_e32 v36, v32, v32
	v_mul_f32_e64 v32, |v32|, s89
	v_exp_f32_e32 v32, v32
	v_mul_f32_e64 v37, |v33|, s89
	v_exp_f32_e32 v37, v37
	v_min_f32_e32 v36, 0, v36
	v_add_f32_e32 v32, 1.0, v32
	v_add_f32_e32 v37, 1.0, v37
	v_log_f32_e32 v32, v32
	v_log_f32_e32 v37, v37
	v_mul_f32_e32 v39, 0x3f317217, v32
	v_fma_f32 v39, v32, s91, -v39
	v_fmac_f32_e32 v39, 0x3377d1cf, v32
	v_fmac_f32_e32 v39, 0x3f317217, v32
	v_max_f32_e32 v33, v33, v33
	v_min_f32_e32 v33, 0, v33
	v_mov_b32_e32 v32, v39
	v_sub_f32_e32 v32, v36, v32
	v_mul_f32_e32 v36, 0x3f317217, v37
	v_fma_f32 v36, v37, s91, -v36
	v_fmac_f32_e32 v36, 0x3377d1cf, v37
	v_fmac_f32_e32 v36, 0x3f317217, v37
	v_fma_f32 v32, v32, s93, 0
	v_mul_f32_e64 v37, |v34|, s89
	v_exp_f32_e32 v37, v37
	v_sub_f32_e32 v33, v33, v36
	v_mov_b32_e32 v39, 0
	v_add_f32_e32 v36, 1.0, v37
	s_nop 1
	v_log_f32_e32 v36, v36
	v_fmamk_f32 v37, v33, 0x3d800000, v32
	v_max_f32_e32 v33, v34, v34
	v_mul_f32_e32 v34, 0x3f317217, v36
	v_fma_f32 v34, v36, s91, -v34
	v_fmac_f32_e32 v34, 0x3377d1cf, v36
	v_fmac_f32_e32 v34, 0x3f317217, v36
	v_min_f32_e32 v33, 0, v33
	s_nop 0
	v_mul_f32_e64 v36, |v35|, s89
	v_exp_f32_e32 v36, v36
	v_sub_f32_e32 v33, v33, v34
	v_add_u32_e32 v38, 0x8800, v98
	v_add_f32_e32 v34, 1.0, v36
	s_nop 1
	v_log_f32_e32 v34, v34
	v_fmamk_f32 v36, v33, 0x3d800000, v37
	v_max_f32_e32 v33, v35, v35
	v_min_f32_e32 v33, 0, v33
	v_mul_f32_e32 v35, 0x3f317217, v34
	v_fma_f32 v35, v34, s91, -v35
	v_fmac_f32_e32 v35, 0x3377d1cf, v34
	v_fmac_f32_e32 v35, 0x3f317217, v34
	s_nop 1
	v_mov_b32_e32 v34, v35
	v_sub_f32_e32 v33, v33, v34
	v_fmamk_f32 v34, v33, 0x3d800000, v36
	ds_bpermute_b32 v33, v83, v34
	s_waitcnt lgkmcnt(0)
	v_cndmask_b32_e64 v33, v33, 0, s[8:9]
	v_add_f32_e32 v33, v33, v34
	ds_bpermute_b32 v35, v84, v33
	s_waitcnt lgkmcnt(0)
	v_cndmask_b32_e64 v35, 0, v35, s[10:11]
	v_add_f32_e32 v33, v35, v33
	v_sub_f32_e32 v35, v33, v34
	ds_bpermute_b32 v33, v85, v33
	v_add_f32_e32 v35, 0, v35
	v_add_f32_e32 v32, v32, v35
	v_add_f32_e32 v37, v37, v35
	ds_write2_b32 v38, v32, v37 offset1:132
	v_add_f32_e32 v32, v36, v35
	v_add_f32_e32 v34, v34, v35
	v_add_u32_e32 v35, 0x8c00, v98
	ds_write2_b32 v35, v32, v34 offset0:8 offset1:140
	v_mov_b32_e32 v32, 0
	v_mov_b32_e32 v34, 0
	v_mov_b32_e32 v35, 0
	v_mov_b32_e32 v36, 0
	v_mov_b32_e32 v37, 0
	v_mov_b32_e32 v38, 0
	v_mov_b32_e32 v108, 0
	v_mov_b32_e32 v109, 0
	v_mov_b32_e32 v110, 0
	v_mov_b32_e32 v111, 0
	v_mov_b32_e32 v112, 0
	v_mov_b32_e32 v113, 0
	v_mov_b32_e32 v114, 0
	v_mov_b32_e32 v115, 0
	s_and_saveexec_b64 s[36:37], s[6:7]
	s_cbranch_execz .LBB0_488
	ds_read_b128 v[34:37], v96 offset:1024
	ds_read_b128 v[38:41], v96 offset:1040
	s_waitcnt lgkmcnt(1)
	v_cvt_pk_bf16_f32 v112, v34, v35
	v_lshlrev_b32_e32 v132, 16, v112
	v_and_b32_e32 v133, 0xffff0000, v112
	v_pk_add_f32 v[34:35], v[34:35], v[132:133] neg_lo:[0,1] neg_hi:[0,1]
	v_cvt_pk_bf16_f32 v113, v36, v37
	v_lshlrev_b32_e32 v134, 16, v113
	v_and_b32_e32 v135, 0xffff0000, v113
	v_pk_add_f32 v[36:37], v[36:37], v[134:135] neg_lo:[0,1] neg_hi:[0,1]
	s_waitcnt lgkmcnt(0)
	v_cvt_pk_bf16_f32 v114, v38, v39
	v_lshlrev_b32_e32 v136, 16, v114
	v_and_b32_e32 v137, 0xffff0000, v114
	v_pk_add_f32 v[38:39], v[38:39], v[136:137] neg_lo:[0,1] neg_hi:[0,1]
	v_cvt_pk_bf16_f32 v115, v40, v41
	v_lshlrev_b32_e32 v138, 16, v115
	v_and_b32_e32 v139, 0xffff0000, v115
	v_pk_add_f32 v[40:41], v[40:41], v[138:139] neg_lo:[0,1] neg_hi:[0,1]
	s_nop 0
	v_cvt_pk_bf16_f32 v111, v40, v41
	v_cvt_pk_bf16_f32 v110, v38, v39
	v_cvt_pk_bf16_f32 v109, v36, v37
	v_cvt_pk_bf16_f32 v108, v34, v35
.LBB0_488:
	s_or_b64 exec, exec, s[36:37]
	s_nop 0
	v_mfma_f32_16x16x32_bf16 v[34:37], v[108:111], v[20:23], v[28:31]
	v_mfma_f32_16x16x32_bf16 v[34:37], v[112:115], v[24:27], v[34:37]
	v_mfma_f32_16x16x32_bf16 v[34:37], v[112:115], v[20:23], v[34:37]
	s_nop 7
	v_max_f32_e32 v38, v34, v34
	v_mul_f32_e64 v34, |v34|, s89
	v_exp_f32_e32 v34, v34
	v_mul_f32_e64 v39, |v35|, s89
	v_exp_f32_e32 v39, v39
	v_min_f32_e32 v38, 0, v38
	v_add_f32_e32 v34, 1.0, v34
	v_add_f32_e32 v39, 1.0, v39
	v_log_f32_e32 v34, v34
	v_log_f32_e32 v39, v39
	v_mul_f32_e32 v41, 0x3f317217, v34
	v_fma_f32 v41, v34, s91, -v41
	v_fmac_f32_e32 v41, 0x3377d1cf, v34
	v_fmac_f32_e32 v41, 0x3f317217, v34
	v_mul_f32_e32 v42, 0x3f317217, v39
	v_max_f32_e32 v35, v35, v35
	v_mov_b32_e32 v34, v41
	v_sub_f32_e32 v34, v38, v34
	v_fma_f32 v38, v39, s91, -v42
	v_fmac_f32_e32 v38, 0x3377d1cf, v39
	v_fmac_f32_e32 v38, 0x3f317217, v39
	v_min_f32_e32 v35, 0, v35
	v_mul_f32_e64 v39, |v36|, s89
	v_exp_f32_e32 v39, v39
	v_sub_f32_e32 v35, v35, v38
	v_max_f32_e32 v36, v36, v36
	v_add_f32_e32 v38, 1.0, v39
	v_min_f32_e32 v36, 0, v36
	v_fma_f32 v34, v34, s93, 0
	v_log_f32_e32 v38, v38
	v_fmamk_f32 v35, v35, 0x3d800000, v34
	v_mul_f32_e32 v39, 0x3f317217, v38
	v_fma_f32 v39, v38, s91, -v39
	v_fmac_f32_e32 v39, 0x3377d1cf, v38
	v_fmac_f32_e32 v39, 0x3f317217, v38
	s_nop 1
	v_mov_b32_e32 v38, v39
	v_mul_f32_e64 v39, |v37|, s89
	v_exp_f32_e32 v39, v39
	v_sub_f32_e32 v36, v36, v38
	v_max_f32_e32 v37, v37, v37
	v_add_f32_e32 v38, 1.0, v39
	v_min_f32_e32 v37, 0, v37
	v_fmamk_f32 v36, v36, 0x3d800000, v35
	v_log_f32_e32 v38, v38
	s_waitcnt lgkmcnt(2)
; #define LAS __attribute__((address_space(3)))
; __device__ __forceinline__ float bf2f(unsigned b) { return __uint_as_float(b << 16); }
; __device__ __forceinline__ unsigned f2bf(float f) { unsigned u = __float_as_uint(f); return (u + 0x7fffu + ((u >> 16) & 1u)) >> 16; }
; __device__ __forceinline__ void split8(const f32x4 x0, const f32x4 x1, bf16x8& hi, bf16x8& lo) {
; #pragma unroll
;     for (int j = 0; j < 8; ++j) { const float x = j < 4 ? x0[j & 3] : x1[j & 3]; const unsigned h = f2bf(x); const unsigned l = f2bf(x - bf2f(h)); hi[j] = (short)h; lo[j] = (short)l; }
; }
; __device__ __forceinline__ void phase_gla_pre(const Params& P, LAS unsigned char* lds, bool dry) {
;     ...
;             if (g < 2) { const f32x4 l0 = *(const LAS f32x4*)(Llr + (16 * tt + fr) * 16 + 8 * g), l1 = *(const LAS f32x4*)(Llr + (16 * tt + fr) * 16 + 8 * g + 4); split8(l0, l1, ahi, alo); }
;             f32x4 acc = (f32x4){bg, bg, bg, bg};
;             acc = __builtin_amdgcn_mfma_f32_16x16x32_bf16(alo, bhi, acc, 0, 0, 0); acc = __builtin_amdgcn_mfma_f32_16x16x32_bf16(ahi, blo, acc, 0, 0, 0); acc = __builtin_amdgcn_mfma_f32_16x16x32_bf16(ahi, bhi, acc, 0, 0, 0);
;             float pr[4];
; #pragma unroll
;             for (int r = 0; r < 4; ++r) { const float lg = acc[r]; const float ls = fminf(lg, 0.f) - __logf(1.0f + __expf(-fabsf(lg))); pr[r] = ls * (1.0f / 16.0f) + (r ? pr[r - 1] : 0.f); }
;             const float T = pr[3];
;             const float u1 = __shfl_up(T, 16), s1 = T + (g >= 1 ? u1 : 0.f);
;             const float u2 = __shfl_up(s1, 32), s2 = s1 + (g >= 2 ? u2 : 0.f);
;             const float base = run + (s2 - T); run += __shfl(s2, 48 + fr);
; #pragma unroll
;             for (int r = 0; r < 4; ++r) *(LAS float*)(Lb + (16 * tt + 4 * g + r) * BP + (16 * w + fr) * 4) = base + pr[r];
	v_add_f32_e32 v40, 0, v33
	v_mul_f32_e32 v39, 0x3f317217, v38
	v_fma_f32 v39, v38, s91, -v39
	v_fmac_f32_e32 v39, 0x3377d1cf, v38
	v_fmac_f32_e32 v39, 0x3f317217, v38
	s_nop 1
	v_mov_b32_e32 v38, v39
	v_sub_f32_e32 v37, v37, v38
	v_fmamk_f32 v37, v37, 0x3d800000, v36
	ds_bpermute_b32 v38, v83, v37
	s_waitcnt lgkmcnt(0)
	v_cndmask_b32_e64 v38, v38, 0, s[8:9]
	v_add_f32_e32 v38, v38, v37
	ds_bpermute_b32 v39, v84, v38
	s_waitcnt lgkmcnt(0)
	v_cndmask_b32_e64 v33, 0, v39, s[10:11]
	v_add_f32_e32 v33, v33, v38
	v_sub_f32_e32 v38, v33, v37
	ds_bpermute_b32 v41, v85, v33
	v_add_f32_e32 v38, v40, v38
	v_add_f32_e32 v33, v34, v38
	v_add_f32_e32 v34, v35, v38
	v_add_u32_e32 v35, 0xa800, v98
	ds_write2_b32 v35, v33, v34 offset0:64 offset1:196
	v_add_f32_e32 v33, v36, v38
	v_add_f32_e32 v34, v37, v38
	v_add_u32_e32 v35, 0xac00, v98
	ds_write2_b32 v35, v33, v34 offset0:72 offset1:204
	v_mov_b32_e32 v33, 0
	v_mov_b32_e32 v34, 0
	v_mov_b32_e32 v35, 0
	v_mov_b32_e32 v36, 0
	v_mov_b32_e32 v37, 0
	v_mov_b32_e32 v38, 0
	v_mov_b32_e32 v39, 0
	v_mov_b32_e32 v116, 0
	v_mov_b32_e32 v117, 0
	v_mov_b32_e32 v118, 0
	v_mov_b32_e32 v119, 0
	v_mov_b32_e32 v120, 0
	v_mov_b32_e32 v121, 0
	v_mov_b32_e32 v122, 0
	v_mov_b32_e32 v123, 0
	s_and_saveexec_b64 s[36:37], s[6:7]
	s_cbranch_execz .LBB0_490
	ds_read_b128 v[32:35], v96 offset:2048
	ds_read_b128 v[36:39], v96 offset:2064
	s_waitcnt lgkmcnt(1)
	v_cvt_pk_bf16_f32 v120, v32, v33
	v_lshlrev_b32_e32 v132, 16, v120
	v_and_b32_e32 v133, 0xffff0000, v120
	v_pk_add_f32 v[32:33], v[32:33], v[132:133] neg_lo:[0,1] neg_hi:[0,1]
	v_cvt_pk_bf16_f32 v121, v34, v35
	v_lshlrev_b32_e32 v134, 16, v121
	v_and_b32_e32 v135, 0xffff0000, v121
	v_pk_add_f32 v[34:35], v[34:35], v[134:135] neg_lo:[0,1] neg_hi:[0,1]
	s_waitcnt lgkmcnt(0)
	v_cvt_pk_bf16_f32 v122, v36, v37
	v_lshlrev_b32_e32 v136, 16, v122
	v_and_b32_e32 v137, 0xffff0000, v122
	v_pk_add_f32 v[36:37], v[36:37], v[136:137] neg_lo:[0,1] neg_hi:[0,1]
	v_cvt_pk_bf16_f32 v123, v38, v39
	v_lshlrev_b32_e32 v138, 16, v123
	v_and_b32_e32 v139, 0xffff0000, v123
	v_pk_add_f32 v[38:39], v[38:39], v[138:139] neg_lo:[0,1] neg_hi:[0,1]
	s_nop 0
	v_cvt_pk_bf16_f32 v119, v38, v39
	v_cvt_pk_bf16_f32 v118, v36, v37
	v_cvt_pk_bf16_f32 v117, v34, v35
	v_cvt_pk_bf16_f32 v116, v32, v33
.LBB0_490:
	s_or_b64 exec, exec, s[36:37]
	s_nop 0
	v_mfma_f32_16x16x32_bf16 v[32:35], v[116:119], v[20:23], v[28:31]
	s_waitcnt lgkmcnt(2)
	v_add_f32_e32 v40, v40, v41
	v_mfma_f32_16x16x32_bf16 v[32:35], v[120:123], v[24:27], v[32:35]
	v_mfma_f32_16x16x32_bf16 v[32:35], v[120:123], v[20:23], v[32:35]
	s_nop 7
	v_max_f32_e32 v36, v32, v32
	v_mul_f32_e64 v32, |v32|, s89
	v_exp_f32_e32 v32, v32
	v_mul_f32_e64 v37, |v33|, s89
	v_exp_f32_e32 v37, v37
	v_min_f32_e32 v36, 0, v36
	v_add_f32_e32 v32, 1.0, v32
	v_add_f32_e32 v37, 1.0, v37
	v_log_f32_e32 v32, v32
	v_log_f32_e32 v37, v37
	v_mul_f32_e32 v39, 0x3f317217, v32
	v_fma_f32 v39, v32, s91, -v39
	v_fmac_f32_e32 v39, 0x3377d1cf, v32
	v_fmac_f32_e32 v39, 0x3f317217, v32
	v_mul_f32_e32 v42, 0x3f317217, v37
	v_max_f32_e32 v33, v33, v33
	v_mov_b32_e32 v32, v39
	v_sub_f32_e32 v32, v36, v32
	v_fma_f32 v36, v37, s91, -v42
	v_fmac_f32_e32 v36, 0x3377d1cf, v37
	v_fmac_f32_e32 v36, 0x3f317217, v37
	v_min_f32_e32 v33, 0, v33
	v_mul_f32_e64 v37, |v34|, s89
	v_exp_f32_e32 v37, v37
	v_sub_f32_e32 v33, v33, v36
	v_max_f32_e32 v34, v34, v34
	v_add_f32_e32 v36, 1.0, v37
	v_min_f32_e32 v34, 0, v34
	v_fma_f32 v32, v32, s93, 0
	v_log_f32_e32 v36, v36
	v_fmamk_f32 v33, v33, 0x3d800000, v32
	v_mov_b32_e32 v39, 0
	v_mul_f32_e32 v37, 0x3f317217, v36
	v_fma_f32 v37, v36, s91, -v37
	v_fmac_f32_e32 v37, 0x3377d1cf, v36
	v_fmac_f32_e32 v37, 0x3f317217, v36
	s_nop 1
	v_mov_b32_e32 v36, v37
	v_mul_f32_e64 v37, |v35|, s89
	v_exp_f32_e32 v37, v37
	v_sub_f32_e32 v34, v34, v36
	v_max_f32_e32 v35, v35, v35
	v_add_f32_e32 v36, 1.0, v37
	v_min_f32_e32 v35, 0, v35
	v_fmamk_f32 v34, v34, 0x3d800000, v33
	v_log_f32_e32 v36, v36
	v_mov_b32_e32 v38, 0
	v_mul_f32_e32 v37, 0x3f317217, v36
	v_fma_f32 v37, v36, s91, -v37
	v_fmac_f32_e32 v37, 0x3377d1cf, v36
	v_fmac_f32_e32 v37, 0x3f317217, v36
	s_nop 1
	v_mov_b32_e32 v36, v37
	v_sub_f32_e32 v35, v35, v36
	v_fmamk_f32 v35, v35, 0x3d800000, v34
	ds_bpermute_b32 v36, v83, v35
	s_waitcnt lgkmcnt(0)
	v_cndmask_b32_e64 v36, v36, 0, s[8:9]
	v_add_f32_e32 v36, v36, v35
	ds_bpermute_b32 v37, v84, v36
	s_waitcnt lgkmcnt(0)
	v_cndmask_b32_e64 v37, 0, v37, s[10:11]
	v_add_f32_e32 v36, v37, v36
	v_sub_f32_e32 v37, v36, v35
	ds_bpermute_b32 v41, v85, v36
	v_add_f32_e32 v37, v40, v37
	v_add_f32_e32 v32, v32, v37
	v_add_f32_e32 v33, v33, v37
	v_add_u32_e32 v36, 0xca00, v98
	ds_write2_b32 v36, v32, v33 offset1:132
	v_add_f32_e32 v32, v34, v37
	v_add_f32_e32 v33, v35, v37
	v_add_u32_e32 v34, 0xce00, v98
	ds_write2_b32 v34, v32, v33 offset0:8 offset1:140
	v_mov_b32_e32 v32, 0
	v_mov_b32_e32 v33, 0
	v_mov_b32_e32 v34, 0
	v_mov_b32_e32 v35, 0
	v_mov_b32_e32 v36, 0
	v_mov_b32_e32 v37, 0
	v_mov_b32_e32 v124, 0
	v_mov_b32_e32 v125, 0
	v_mov_b32_e32 v126, 0
	v_mov_b32_e32 v127, 0
	v_mov_b32_e32 v128, 0
	v_mov_b32_e32 v129, 0
	v_mov_b32_e32 v130, 0
	v_mov_b32_e32 v131, 0
	s_and_saveexec_b64 s[36:37], s[6:7]
	s_cbranch_execz .LBB0_492
	ds_read_b128 v[32:35], v96 offset:3072
	ds_read_b128 v[36:39], v96 offset:3088
	s_waitcnt lgkmcnt(1)
	v_cvt_pk_bf16_f32 v128, v32, v33
	v_lshlrev_b32_e32 v132, 16, v128
	v_and_b32_e32 v133, 0xffff0000, v128
	v_pk_add_f32 v[32:33], v[32:33], v[132:133] neg_lo:[0,1] neg_hi:[0,1]
	v_cvt_pk_bf16_f32 v129, v34, v35
	v_lshlrev_b32_e32 v134, 16, v129
	v_and_b32_e32 v135, 0xffff0000, v129
	v_pk_add_f32 v[34:35], v[34:35], v[134:135] neg_lo:[0,1] neg_hi:[0,1]
	s_waitcnt lgkmcnt(0)
	v_cvt_pk_bf16_f32 v130, v36, v37
	v_lshlrev_b32_e32 v136, 16, v130
	v_and_b32_e32 v137, 0xffff0000, v130
	v_pk_add_f32 v[36:37], v[36:37], v[136:137] neg_lo:[0,1] neg_hi:[0,1]
	v_cvt_pk_bf16_f32 v131, v38, v39
	v_lshlrev_b32_e32 v138, 16, v131
	v_and_b32_e32 v139, 0xffff0000, v131
	v_pk_add_f32 v[38:39], v[38:39], v[138:139] neg_lo:[0,1] neg_hi:[0,1]
	s_nop 0
	v_cvt_pk_bf16_f32 v127, v38, v39
	v_cvt_pk_bf16_f32 v126, v36, v37
	v_cvt_pk_bf16_f32 v125, v34, v35
	v_cvt_pk_bf16_f32 v124, v32, v33
; #define LAS __attribute__((address_space(3)))
; __device__ __forceinline__ float bflo(unsigned w) { return __uint_as_float(w << 16); }
; __device__ __forceinline__ float bfhi(unsigned w) { return __uint_as_float(w & 0xffff0000u); }
; __device__ __forceinline__ void phase_gla_pre(const Params& P, LAS unsigned char* lds, bool dry) {
;     ...
;             acc = __builtin_amdgcn_mfma_f32_16x16x32_bf16(alo, bhi, acc, 0, 0, 0); acc = __builtin_amdgcn_mfma_f32_16x16x32_bf16(ahi, blo, acc, 0, 0, 0); acc = __builtin_amdgcn_mfma_f32_16x16x32_bf16(ahi, bhi, acc, 0, 0, 0);
;             float pr[4];
; #pragma unroll
;             for (int r = 0; r < 4; ++r) { const float lg = acc[r]; const float ls = fminf(lg, 0.f) - __logf(1.0f + __expf(-fabsf(lg))); pr[r] = ls * (1.0f / 16.0f) + (r ? pr[r - 1] : 0.f); }
;             const float T = pr[3];
;             const float u1 = __shfl_up(T, 16), s1 = T + (g >= 1 ? u1 : 0.f);
;             const float u2 = __shfl_up(s1, 32), s2 = s1 + (g >= 2 ? u2 : 0.f);
;             const float base = run + (s2 - T); run += __shfl(s2, 48 + fr);
; #pragma unroll
;             for (int r = 0; r < 4; ++r) *(LAS float*)(Lb + (16 * tt + 4 * g + r) * BP + (16 * w + fr) * 4) = base + pr[r];
;         }
;         __syncthreads();
;         {
;             f32x4 bb[4], bm[4], bl[4];
; #pragma unroll
;             for (int i = 0; i < 4; ++i) { bb[i] = *(const LAS f32x4*)(Lb + te * BP + (16 * kc + 4 * i) * 4); bm[i] = *(const LAS f32x4*)(Lb + 31 * BP + (16 * kc + 4 * i) * 4); bl[i] = *(const LAS f32x4*)(Lb + 63 * BP + (16 * kc + 4 * i) * 4); }
;             unsigned oqi[8], oki[8], oqd[8], oks[8];
; #pragma unroll
;             for (int e2 = 0; e2 < 8; ++e2) {
;                 const unsigned qw = e2 < 4 ? rq[0][e2] : rq[1][e2 - 4], kw = e2 < 4 ? rk[0][e2] : rk[1][e2 - 4];
;                 float vqi[2], vki[2], vqd[2], vks[2];
; #pragma unroll
;                 for (int hh = 0; hh < 2; ++hh) {
;                     const int e = 2 * e2 + hh; const float bv = bb[e >> 2][e & 3], bmv = bm[e >> 2][e & 3], blv = bl[e >> 2][e & 3];
;                     const float qv = hh ? bfhi(qw) : bflo(qw), kv = hh ? bfhi(kw) : bflo(kw);
;                     const float e1 = __expf(bv - bmv);
;                     vqi[hh] = qv * e1; vki[hh] = kv * __builtin_amdgcn_rcpf(e1); vqd[hh] = qv * __expf(bv); vks[hh] = kv * __expf(blv - bv);
;                 }
.LBB0_492:
	s_or_b64 exec, exec, s[36:37]
	s_nop 0
	v_mfma_f32_16x16x32_bf16 v[28:31], v[124:127], v[20:23], v[28:31]
	v_and_b32_e32 v111, 0xffff0000, v5
	v_and_b32_e32 v110, 0xffff0000, v4
	v_and_b32_e32 v117, 0xffff0000, v13
	v_mfma_f32_16x16x32_bf16 v[24:27], v[128:131], v[24:27], v[28:31]
	v_and_b32_e32 v116, 0xffff0000, v12
	v_and_b32_e32 v121, 0xffff0000, v7
	v_and_b32_e32 v120, 0xffff0000, v6
	v_mfma_f32_16x16x32_bf16 v[20:23], v[128:131], v[20:23], v[24:27]
	v_and_b32_e32 v127, 0xffff0000, v17
	v_and_b32_e32 v126, 0xffff0000, v16
	v_lshlrev_b32_e32 v125, 16, v17
	v_lshlrev_b32_e32 v124, 16, v16
	v_lshlrev_b32_e32 v133, 16, v11
	s_nop 2
	v_max_f32_e32 v24, v20, v20
	v_mul_f32_e64 v20, |v20|, s89
	v_exp_f32_e32 v20, v20
	v_mul_f32_e64 v25, |v21|, s89
	v_exp_f32_e32 v25, v25
	v_min_f32_e32 v24, 0, v24
	v_add_f32_e32 v20, 1.0, v20
	v_add_f32_e32 v25, 1.0, v25
	v_log_f32_e32 v20, v20
	v_log_f32_e32 v25, v25
	v_mul_f32_e32 v27, 0x3f317217, v20
	v_fma_f32 v27, v20, s91, -v27
	v_fmac_f32_e32 v27, 0x3377d1cf, v20
	v_fmac_f32_e32 v27, 0x3f317217, v20
	v_mul_f32_e32 v28, 0x3f317217, v25
	v_max_f32_e32 v21, v21, v21
	v_mov_b32_e32 v20, v27
	v_sub_f32_e32 v20, v24, v20
	v_fma_f32 v24, v25, s91, -v28
	v_fmac_f32_e32 v24, 0x3377d1cf, v25
	v_fmac_f32_e32 v24, 0x3f317217, v25
	v_min_f32_e32 v21, 0, v21
	v_mul_f32_e64 v25, |v22|, s89
	v_exp_f32_e32 v25, v25
	v_sub_f32_e32 v21, v21, v24
	v_max_f32_e32 v22, v22, v22
	v_add_f32_e32 v24, 1.0, v25
	v_min_f32_e32 v22, 0, v22
	v_fma_f32 v20, v20, s93, 0
	v_log_f32_e32 v24, v24
	v_fmamk_f32 v21, v21, 0x3d800000, v20
	v_lshlrev_b32_e32 v132, 16, v10
	v_mul_f32_e32 v25, 0x3f317217, v24
	v_fma_f32 v25, v24, s91, -v25
	v_fmac_f32_e32 v25, 0x3377d1cf, v24
	v_fmac_f32_e32 v25, 0x3f317217, v24
	v_and_b32_e32 v135, 0xffff0000, v11
	v_and_b32_e32 v134, 0xffff0000, v10
	v_mov_b32_e32 v24, v25
	v_mul_f32_e64 v25, |v23|, s89
	v_exp_f32_e32 v25, v25
	v_sub_f32_e32 v22, v22, v24
	v_max_f32_e32 v23, v23, v23
	v_add_f32_e32 v24, 1.0, v25
	v_min_f32_e32 v23, 0, v23
	v_fmamk_f32 v22, v22, 0x3d800000, v21
	v_log_f32_e32 v24, v24
	s_waitcnt lgkmcnt(2)
	v_add_f32_e32 v26, v40, v41
	s_and_b32 s74, s1, 0xfc0
	s_ashr_i32 s83, s82, 31
	v_mul_f32_e32 v25, 0x3f317217, v24
	v_fma_f32 v25, v24, s91, -v25
	v_fmac_f32_e32 v25, 0x3377d1cf, v24
	v_fmac_f32_e32 v25, 0x3f317217, v24
	s_nop 1
	v_mov_b32_e32 v24, v25
	v_sub_f32_e32 v23, v23, v24
	v_fmamk_f32 v23, v23, 0x3d800000, v22
	ds_bpermute_b32 v24, v83, v23
	s_lshl_b64 s[36:37], s[82:83], 20
	s_waitcnt lgkmcnt(0)
	v_cndmask_b32_e64 v24, v24, 0, s[8:9]
	v_add_f32_e32 v24, v24, v23
	ds_bpermute_b32 v25, v84, v24
	s_waitcnt lgkmcnt(0)
	v_cndmask_b32_e64 v25, 0, v25, s[10:11]
	v_add_f32_e32 v24, v25, v24
	v_sub_f32_e32 v24, v24, v23
	v_add_f32_e32 v24, v26, v24
	v_add_f32_e32 v20, v20, v24
	v_add_f32_e32 v21, v21, v24
	v_add_u32_e32 v25, 0xea00, v98
	ds_write2_b32 v25, v20, v21 offset0:64 offset1:196
	v_add_f32_e32 v20, v22, v24
	v_add_f32_e32 v21, v23, v24
	v_add_u32_e32 v22, 0xee00, v98
	ds_write2_b32 v22, v20, v21 offset0:72 offset1:204
	v_add_u32_e32 v22, s94, v87
	s_waitcnt lgkmcnt(0)
	s_barrier
	v_add_u32_e32 v20, v86, v87
	v_add_u32_e32 v21, 0, v87
	ds_read_b128 v[32:35], v22
	ds_read_b128 v[24:27], v89
	ds_read_b128 v[60:63], v21 offset:51184
	ds_read_b128 v[64:67], v20 offset:34816
	ds_read_b128 v[74:77], v20 offset:34832
	ds_read_b128 v[44:47], v20 offset:34848
	ds_read_b128 v[36:39], v20 offset:34864
	ds_read_b128 v[100:103], v21 offset:51200
	s_waitcnt lgkmcnt(4)
	v_sub_f32_e32 v61, v65, v61
	v_mul_f32_e32 v61, 0x3fb8aa3b, v61
	v_sub_f32_e32 v63, v67, v63
	v_exp_f32_e32 v72, v61
	v_sub_f32_e32 v61, v32, v64
	v_mul_f32_e32 v63, 0x3fb8aa3b, v63
	v_mul_f32_e32 v61, 0x3fb8aa3b, v61
	v_exp_f32_e32 v73, v63
	v_exp_f32_e32 v78, v61
	v_mul_f32_e32 v61, 0x3fb8aa3b, v65
	v_sub_f32_e32 v20, v64, v60
	v_exp_f32_e32 v108, v61
	v_sub_f32_e32 v61, v66, v62
	v_mul_f32_e32 v20, 0x3fb8aa3b, v20
	v_mul_f32_e32 v69, 0x3fb8aa3b, v64
	v_mul_f32_e32 v61, 0x3fb8aa3b, v61
	v_sub_f32_e32 v62, v33, v65
	v_mul_f32_e32 v65, 0x3fb8aa3b, v66
	v_sub_f32_e32 v63, v34, v66
	v_exp_f32_e32 v60, v20
	v_exp_f32_e32 v70, v69
	v_rcp_f32_e32 v64, v72
	v_exp_f32_e32 v61, v61
	v_exp_f32_e32 v71, v65
	v_mul_f32_e32 v63, 0x3fb8aa3b, v63
	v_rcp_f32_e32 v65, v73
	v_exp_f32_e32 v79, v63
	v_mul_f32_e32 v63, 0x3fb8aa3b, v67
	v_exp_f32_e32 v109, v63
	v_sub_f32_e32 v63, v35, v67
	v_lshlrev_b32_e32 v67, 16, v5
	v_lshlrev_b32_e32 v66, 16, v4
	v_pk_mul_f32 v[112:113], v[60:61], v[66:67]
	v_pk_mul_f32 v[114:115], v[72:73], v[110:111]
	v_pk_mul_f32 v[72:73], v[64:65], v[116:117]
	v_pk_mul_f32 v[64:65], v[70:71], v[66:67]
	s_waitcnt lgkmcnt(0)
; __device__ __forceinline__ float bflo(unsigned w) { return __uint_as_float(w << 16); }
; __device__ __forceinline__ float bfhi(unsigned w) { return __uint_as_float(w & 0xffff0000u); }
; __device__ __forceinline__ unsigned pk2(float lo, float hi) { return f2bf(lo) | (f2bf(hi) << 16); }
; __device__ __forceinline__ void phase_gla_pre(const Params& P, LAS unsigned char* lds, bool dry) {
;     ...
;             for (int e2 = 0; e2 < 8; ++e2) {
;                 const unsigned qw = e2 < 4 ? rq[0][e2] : rq[1][e2 - 4], kw = e2 < 4 ? rk[0][e2] : rk[1][e2 - 4];
;                 float vqi[2], vki[2], vqd[2], vks[2];
; #pragma unroll
;                 for (int hh = 0; hh < 2; ++hh) {
;                     const int e = 2 * e2 + hh; const float bv = bb[e >> 2][e & 3], bmv = bm[e >> 2][e & 3], blv = bl[e >> 2][e & 3];
;                     const float qv = hh ? bfhi(qw) : bflo(qw), kv = hh ? bfhi(kw) : bflo(kw);
;                     const float e1 = __expf(bv - bmv);
;                     vqi[hh] = qv * e1; vki[hh] = kv * __builtin_amdgcn_rcpf(e1); vqd[hh] = qv * __expf(bv); vks[hh] = kv * __expf(blv - bv);
;                 }
;                 oqi[e2] = pk2(vqi[0], vqi[1]); oki[e2] = pk2(vki[0], vki[1]); oqd[e2] = pk2(vqd[0], vqd[1]); oks[e2] = pk2(vks[0], vks[1]);
	v_sub_f32_e32 v66, v74, v100
	v_mul_f32_e32 v66, 0x3fb8aa3b, v66
	v_mul_f32_e32 v71, 0x3fb8aa3b, v74
	v_exp_f32_e32 v70, v66
	v_pk_mul_f32 v[66:67], v[108:109], v[110:111]
	v_exp_f32_e32 v108, v71
	v_sub_f32_e32 v71, v75, v101
	v_mul_f32_e32 v71, 0x3fb8aa3b, v71
	v_mul_f32_e32 v62, 0x3fb8aa3b, v62
	v_mul_f32_e32 v63, 0x3fb8aa3b, v63
	v_exp_f32_e32 v100, v71
	v_sub_f32_e32 v71, v24, v74
	v_exp_f32_e32 v62, v62
	v_exp_f32_e32 v63, v63
	v_mul_f32_e32 v71, 0x3fb8aa3b, v71
	v_exp_f32_e32 v74, v71
	v_mul_f32_e32 v71, 0x3fb8aa3b, v75
	v_sub_f32_e32 v75, v25, v75
	v_mul_f32_e32 v75, 0x3fb8aa3b, v75
	v_exp_f32_e32 v118, v75
	v_mul_f32_e32 v75, 0x3fb8aa3b, v76
	v_pk_mul_f32 v[62:63], v[62:63], v[116:117]
	v_exp_f32_e32 v116, v71
	v_sub_f32_e32 v71, v76, v102
	v_exp_f32_e32 v109, v75
	v_sub_f32_e32 v75, v77, v103
	v_mul_f32_e32 v71, 0x3fb8aa3b, v71
	v_mul_f32_e32 v75, 0x3fb8aa3b, v75
	v_rcp_f32_e32 v68, v60
	v_rcp_f32_e32 v69, v61
	v_exp_f32_e32 v71, v71
	v_exp_f32_e32 v101, v75
	v_sub_f32_e32 v75, v26, v76
	v_mul_f32_e32 v76, 0x3fb8aa3b, v77
	v_exp_f32_e32 v117, v76
	v_sub_f32_e32 v76, v27, v77
	v_mul_f32_e32 v76, 0x3fb8aa3b, v76
	v_lshlrev_b32_e32 v61, 16, v13
	v_lshlrev_b32_e32 v60, 16, v12
	v_exp_f32_e32 v119, v76
	v_lshlrev_b32_e32 v77, 16, v7
	v_lshlrev_b32_e32 v76, 16, v6
	v_pk_mul_f32 v[68:69], v[68:69], v[60:61]
	v_pk_mul_f32 v[60:61], v[78:79], v[60:61]
	v_rcp_f32_e32 v78, v70
	v_rcp_f32_e32 v110, v100
	v_rcp_f32_e32 v79, v71
	v_rcp_f32_e32 v111, v101
	v_pk_mul_f32 v[70:71], v[70:71], v[76:77]
	v_pk_mul_f32 v[100:101], v[100:101], v[120:121]
	v_cvt_pk_bf16_f32 v224, v112, v114
	v_cvt_pk_bf16_f32 v222, v113, v115
	v_cvt_pk_bf16_f32 v221, v70, v100
	v_cvt_pk_bf16_f32 v220, v71, v101
	ds_read_b128 v[104:107], v21 offset:51216
	ds_read_b128 v[40:43], v21 offset:51232
	ds_read_b128 v[28:31], v90
	ds_read_b128 v[20:23], v91
	v_mov_b32_e32 v103, v220
	v_mov_b32_e32 v102, v221
	v_lshlrev_b32_e32 v71, 16, v15
	v_lshlrev_b32_e32 v70, 16, v14
	v_mul_f32_e32 v75, 0x3fb8aa3b, v75
	v_mov_b32_e32 v101, v222
	v_mov_b32_e32 v100, v224
	v_pk_mul_f32 v[114:115], v[78:79], v[70:71]
	s_waitcnt lgkmcnt(3)
	v_sub_f32_e32 v78, v44, v104
	v_sub_f32_e32 v105, v45, v105
	v_exp_f32_e32 v75, v75
	v_mul_f32_e32 v78, 0x3fb8aa3b, v78
	v_mul_f32_e32 v105, 0x3fb8aa3b, v105
	v_exp_f32_e32 v104, v78
	v_pk_mul_f32 v[78:79], v[116:117], v[120:121]
	v_exp_f32_e32 v116, v105
	v_mul_f32_e32 v105, 0x3fb8aa3b, v45
	s_waitcnt lgkmcnt(1)
	v_sub_f32_e32 v45, v29, v45
	v_mul_f32_e32 v45, 0x3fb8aa3b, v45
	v_and_b32_e32 v113, 0xffff0000, v15
	v_and_b32_e32 v112, 0xffff0000, v14
	v_exp_f32_e32 v120, v105
	v_sub_f32_e32 v105, v46, v106
	v_exp_f32_e32 v106, v45
	v_mul_f32_e32 v45, 0x3fb8aa3b, v46
	v_pk_mul_f32 v[110:111], v[110:111], v[112:113]
	v_pk_mul_f32 v[70:71], v[74:75], v[70:71]
	v_pk_mul_f32 v[74:75], v[118:119], v[112:113]
	v_exp_f32_e32 v113, v45
	v_sub_f32_e32 v45, v47, v107
	v_mul_f32_e32 v45, 0x3fb8aa3b, v45
	v_exp_f32_e32 v117, v45
	v_sub_f32_e32 v45, v30, v46
	v_mul_f32_e32 v46, 0x3fb8aa3b, v47
	v_exp_f32_e32 v121, v46
	v_sub_f32_e32 v46, v31, v47
	v_pk_mul_f32 v[76:77], v[108:109], v[76:77]
	v_mul_f32_e32 v109, 0x3fb8aa3b, v44
	v_mul_f32_e32 v105, 0x3fb8aa3b, v105
	v_mul_f32_e32 v46, 0x3fb8aa3b, v46
	v_exp_f32_e32 v112, v109
	v_exp_f32_e32 v105, v105
	v_exp_f32_e32 v107, v46
	v_rcp_f32_e32 v118, v116
	v_rcp_f32_e32 v119, v117
	v_sub_f32_e32 v44, v28, v44
	v_lshlrev_b32_e32 v47, 16, v9
	v_lshlrev_b32_e32 v46, 16, v8
	v_rcp_f32_e32 v108, v104
	v_mul_f32_e32 v44, 0x3fb8aa3b, v44
	v_rcp_f32_e32 v109, v105
	v_mul_f32_e32 v45, 0x3fb8aa3b, v45
	v_pk_mul_f32 v[104:105], v[104:105], v[46:47]
	v_pk_mul_f32 v[112:113], v[112:113], v[46:47]
	v_sub_f32_e32 v40, v36, v40
	v_pk_mul_f32 v[46:47], v[106:107], v[126:127]
	v_mul_f32_e32 v107, 0x3fb8aa3b, v36
	s_waitcnt lgkmcnt(0)
; #define LAS __attribute__((address_space(3)))
; __device__ __forceinline__ unsigned pk2(float lo, float hi) { return f2bf(lo) | (f2bf(hi) << 16); }
; __device__ __forceinline__ void phase_gla_pre(const Params& P, LAS unsigned char* lds, bool dry) {
;     ...
;                 oqi[e2] = pk2(vqi[0], vqi[1]); oki[e2] = pk2(vki[0], vki[1]); oqd[e2] = pk2(vqd[0], vqd[1]); oks[e2] = pk2(vks[0], vks[1]);
;             }
;             *(LAS u32x4*)(Lqi + te * QP + 32 * kc) = (u32x4){oqi[0], oqi[1], oqi[2], oqi[3]}; *(LAS u32x4*)(Lqi + te * QP + 32 * kc + 16) = (u32x4){oqi[4], oqi[5], oqi[6], oqi[7]};
;             *(LAS u32x4*)(Lki + te * QP + 32 * kc) = (u32x4){oki[0], oki[1], oki[2], oki[3]}; *(LAS u32x4*)(Lki + te * QP + 32 * kc + 16) = (u32x4){oki[4], oki[5], oki[6], oki[7]};
;             if (!dry) {
;                 bf16_t* p_ = PJ + ((size_t)bh * SEQ + c * 64 + te) * 128 + 16 * kc;
;                 *(u32x4*)(p_ + T_Q) = (u32x4){oqd[0], oqd[1], oqd[2], oqd[3]}; *(u32x4*)(p_ + T_Q + 8) = (u32x4){oqd[4], oqd[5], oqd[6], oqd[7]};
;                 *(u32x4*)(p_ + T_K) = (u32x4){oks[0], oks[1], oks[2], oks[3]}; *(u32x4*)(p_ + T_K + 8) = (u32x4){oks[4], oks[5], oks[6], oks[7]};
;                 if (te == 63) {
; #pragma unroll
;                     for (int i = 0; i < 4; ++i) *(f32x4*)(DEC + (size_t)item * 128 + 16 * kc + 4 * i) = (f32x4){__expf(bl[i][0]), __expf(bl[i][1]), __expf(bl[i][2]), __expf(bl[i][3])};
;                 }
	v_sub_f32_e32 v36, v20, v36
	v_exp_f32_e32 v44, v44
	v_exp_f32_e32 v45, v45
	v_mul_f32_e32 v36, 0x3fb8aa3b, v36
	v_pk_mul_f32 v[118:119], v[118:119], v[126:127]
	v_exp_f32_e32 v126, v36
	v_mul_f32_e32 v36, 0x3fb8aa3b, v37
	v_sub_f32_e32 v41, v37, v41
	v_exp_f32_e32 v130, v36
	v_sub_f32_e32 v36, v38, v42
	v_mul_f32_e32 v41, 0x3fb8aa3b, v41
	v_mul_f32_e32 v36, 0x3fb8aa3b, v36
	v_pk_mul_f32 v[108:109], v[108:109], v[124:125]
	v_pk_mul_f32 v[44:45], v[44:45], v[124:125]
	v_exp_f32_e32 v124, v41
	v_exp_f32_e32 v41, v36
	v_sub_f32_e32 v36, v21, v37
	v_mul_f32_e32 v36, 0x3fb8aa3b, v36
	v_and_b32_e32 v123, 0xffff0000, v9
	v_and_b32_e32 v122, 0xffff0000, v8
	v_exp_f32_e32 v42, v36
	v_mul_f32_e32 v36, 0x3fb8aa3b, v38
	v_pk_mul_f32 v[116:117], v[116:117], v[122:123]
	v_pk_mul_f32 v[120:121], v[120:121], v[122:123]
	v_exp_f32_e32 v123, v36
	v_sub_f32_e32 v36, v39, v43
	v_mul_f32_e32 v36, 0x3fb8aa3b, v36
	v_mul_f32_e32 v40, 0x3fb8aa3b, v40
	v_exp_f32_e32 v125, v36
	v_sub_f32_e32 v36, v22, v38
	v_exp_f32_e32 v40, v40
	v_mul_f32_e32 v36, 0x3fb8aa3b, v36
	v_exp_f32_e32 v127, v36
	v_mul_f32_e32 v36, 0x3fb8aa3b, v39
	v_exp_f32_e32 v131, v36
	v_sub_f32_e32 v36, v23, v39
	v_mul_f32_e32 v36, 0x3fb8aa3b, v36
	v_rcp_f32_e32 v128, v124
	v_rcp_f32_e32 v129, v125
	v_exp_f32_e32 v43, v36
	v_pk_mul_f32 v[36:37], v[40:41], v[132:133]
	v_pk_mul_f32 v[38:39], v[124:125], v[134:135]
	v_rcp_f32_e32 v106, v40
	v_exp_f32_e32 v122, v107
	v_rcp_f32_e32 v107, v41
	v_cvt_pk_bf16_f32 v228, v104, v116
	v_cvt_pk_bf16_f32 v227, v105, v117
	v_cvt_pk_bf16_f32 v226, v36, v38
	v_cvt_pk_bf16_f32 v225, v37, v39
	v_mov_b32_e32 v39, v225
	v_mov_b32_e32 v38, v226
	v_mov_b32_e32 v37, v227
	v_mov_b32_e32 v36, v228
	ds_write_b128 v92, v[100:103]
	ds_write_b128 v92, v[36:39] offset:16
	v_cvt_pk_bf16_f32 v230, v68, v72
	v_cvt_pk_bf16_f32 v229, v69, v73
	v_lshlrev_b32_e32 v41, 16, v19
	v_lshlrev_b32_e32 v40, 16, v18
	v_cvt_pk_bf16_f32 v39, v115, v111
	v_cvt_pk_bf16_f32 v38, v114, v110
	v_mov_b32_e32 v37, v229
	v_mov_b32_e32 v36, v230
	v_and_b32_e32 v105, 0xffff0000, v19
	v_and_b32_e32 v104, 0xffff0000, v18
	v_pk_mul_f32 v[106:107], v[106:107], v[40:41]
	ds_write_b128 v92, v[36:39] offset:17408
	v_pk_mul_f32 v[116:117], v[128:129], v[104:105]
	s_nop 0
	v_cvt_pk_bf16_f32 v39, v107, v117
	v_cvt_pk_bf16_f32 v38, v106, v116
	v_cvt_pk_bf16_f32 v37, v109, v119
	v_cvt_pk_bf16_f32 v36, v108, v118
	ds_write_b128 v92, v[36:39] offset:17424
	v_lshl_add_u64 v[36:37], s[74:75], 0, v[48:49]
	v_lshlrev_b64 v[36:37], 8, v[36:37]
	v_lshl_add_u64 v[38:39], v[52:53], 0, s[36:37]
	v_lshl_add_u64 v[68:69], v[38:39], 0, v[36:37]
	v_cvt_pk_bf16_f32 v232, v64, v66
	v_cvt_pk_bf16_f32 v233, v65, v67
	s_brev_b32 s36, 16
	v_cvt_pk_bf16_f32 v39, v77, v79
	v_mov_b32_e32 v36, v232
	v_add_co_u32_e32 v64, vcc, s36, v68
	v_cvt_pk_bf16_f32 v38, v76, v78
	v_mov_b32_e32 v37, v233
	v_addc_co_u32_e32 v65, vcc, 0, v69, vcc
	v_pk_mul_f32 v[122:123], v[122:123], v[132:133]
	global_store_dwordx4 v[64:65], v[36:39], off
	v_pk_mul_f32 v[124:125], v[130:131], v[134:135]
	s_nop 0
	v_cvt_pk_bf16_f32 v39, v123, v125
	v_cvt_pk_bf16_f32 v38, v122, v124
	v_cvt_pk_bf16_f32 v37, v113, v121
	v_cvt_pk_bf16_f32 v36, v112, v120
	global_store_dwordx4 v[64:65], v[36:39], off offset:16
	s_nop 1
	s_nop 0
	v_cvt_pk_bf16_f32 v234, v60, v62
	v_cvt_pk_bf16_f32 v235, v61, v63
	v_cvt_pk_bf16_f32 v39, v71, v75
	v_mov_b32_e32 v36, v234
	v_add_co_u32_e32 v60, vcc, s95, v68
	v_pk_mul_f32 v[42:43], v[42:43], v[104:105]
	v_cvt_pk_bf16_f32 v38, v70, v74
	v_mov_b32_e32 v37, v235
	v_addc_co_u32_e32 v61, vcc, 0, v69, vcc
	v_pk_mul_f32 v[40:41], v[126:127], v[40:41]
	global_store_dwordx4 v[60:61], v[36:39], off
	s_nop 1
	v_cvt_pk_bf16_f32 v240, v44, v46
	v_cvt_pk_bf16_f32 v239, v45, v47
	v_cvt_pk_bf16_f32 v238, v40, v42
	v_cvt_pk_bf16_f32 v237, v41, v43
	v_mov_b32_e32 v39, v237
	v_mov_b32_e32 v38, v238
	v_mov_b32_e32 v37, v239
	v_mov_b32_e32 v36, v240
	global_store_dwordx4 v[60:61], v[36:39], off offset:16
	s_and_saveexec_b64 s[36:37], s[12:13]
	s_cbranch_execz .LBB0_494
	v_mul_f32_e32 v32, 0x3fb8aa3b, v32
	v_mul_f32_e32 v33, 0x3fb8aa3b, v33
	v_mul_f32_e32 v34, 0x3fb8aa3b, v34
	v_mul_f32_e32 v35, 0x3fb8aa3b, v35
	v_exp_f32_e32 v32, v32
	v_exp_f32_e32 v33, v33
	v_exp_f32_e32 v34, v34
	v_exp_f32_e32 v35, v35
	v_mul_f32_e32 v24, 0x3fb8aa3b, v24
	v_mul_f32_e32 v25, 0x3fb8aa3b, v25
	v_mul_f32_e32 v26, 0x3fb8aa3b, v26
	v_mul_f32_e32 v27, 0x3fb8aa3b, v27
	s_ashr_i32 s81, s80, 31
	v_exp_f32_e32 v24, v24
	v_exp_f32_e32 v25, v25
	v_exp_f32_e32 v26, v26
	v_exp_f32_e32 v27, v27
	v_mul_f32_e32 v28, 0x3fb8aa3b, v28
	v_mul_f32_e32 v29, 0x3fb8aa3b, v29
	v_mul_f32_e32 v30, 0x3fb8aa3b, v30
	v_mul_f32_e32 v31, 0x3fb8aa3b, v31
	s_lshl_b64 s[42:43], s[80:81], 9
	v_exp_f32_e32 v28, v28
	v_exp_f32_e32 v29, v29
	v_exp_f32_e32 v30, v30
	v_exp_f32_e32 v31, v31
	v_mul_f32_e32 v20, 0x3fb8aa3b, v20
	v_mul_f32_e32 v21, 0x3fb8aa3b, v21
	v_mul_f32_e32 v22, 0x3fb8aa3b, v22
	v_mul_f32_e32 v23, 0x3fb8aa3b, v23
	v_lshl_add_u64 v[36:37], v[54:55], 0, s[42:43]
	v_exp_f32_e32 v20, v20
	v_exp_f32_e32 v21, v21
	v_exp_f32_e32 v22, v22
	v_exp_f32_e32 v23, v23
	global_store_dwordx4 v[36:37], v[32:35], off
	global_store_dwordx4 v[36:37], v[24:27], off offset:16
	global_store_dwordx4 v[36:37], v[28:31], off offset:32
	global_store_dwordx4 v[36:37], v[20:23], off offset:48
